# staged epilogue constants extended to kind 2 (qkv) with SCC-safe VALU setup
# speedup vs baseline: 1.0117x; 1.0113x over previous
; __device__ __forceinline__ unsigned cvt_pk_bf16(float lo, float hi) { unsigned r; asm volatile("v_cvt_pk_bf16_f32 %0, %1, %2" : "=v"(r) : "v"(lo), "v"(hi)); return r; }
;     __device__ __forceinline__ void operator()(const f32x4 (&acc)[2][2][4][2], const Unit& u, int wr, int wc, int fr, int fq) const {
;         const int row0 = u.pm * BM + wr * 64 + fr, col0 = u.pn * BM + wc * 32 + 8 * fq;
;         f32x4 bv[2][2];
; #pragma unroll
;         for (int bj = 0; bj < 2; ++bj)
; #pragma unroll
;             for (int n = 0; n < 2; ++n) bv[bj][n] = *(const f32x4*)(cb + col0 + bj * HALF + 4 * n);
;         const float sc = (u.pn < 4) ? qscale : 1.f;
;         float sq[2][4];
; #pragma unroll
;         for (int ai = 0; ai < 2; ++ai)
; #pragma unroll
;             for (int m = 0; m < 4; ++m) sq[ai][m] = ssq[row0 + ai * HALF + m * 16];
; #pragma unroll
;         for (int ai = 0; ai < 2; ++ai)
; #pragma unroll
;             for (int m = 0; m < 4; ++m) {
;                 const int row = row0 + ai * HALF + m * 16;
;                 const float rs = __builtin_amdgcn_rsqf(sq[ai][m] * (1.0f / 1024.0f) + RMS_EPS_F);
; #pragma unroll
;                 for (int bj = 0; bj < 2; ++bj) {
;                     const f32x4 v0 = (acc[ai][bj][m][0] * rs + bv[bj][0]) * sc, v1 = (acc[ai][bj][m][1] * rs + bv[bj][1]) * sc;
;                     u32x4 w; w.x = cvt_pk_bf16(v0[0], v0[1]); w.y = cvt_pk_bf16(v0[2], v0[3]); w.z = cvt_pk_bf16(v1[0], v1[1]); w.w = cvt_pk_bf16(v1[2], v1[3]);
;                     *(u32x4*)(O + ((unsigned)row * 3072u + (unsigned)(col0 + bj * HALF))) = w;
;                 }
.LBB0_504:
	s_and_b64 vcc, exec, s[42:43]
	s_cbranch_vccz .LBB0_506
	v_lshl_or_b32 v146, s15, 8, v229
	v_lshl_add_u32 v148, s14, 8, v1
	s_mov_b64 s[44:45], s[72:73]
	s_mov_b64 s[42:43], s[24:25]
	s_mov_b64 s[60:61], s[76:77]
	v_ashrrev_i32_e32 v147, 31, v146
	v_ashrrev_i32_e32 v149, 31, v148
	s_cmp_lt_i32 s15, 4
	v_lshl_add_u64 v[134:135], v[146:147], 2, s[60:61]
	v_lshl_add_u64 v[150:151], v[148:149], 2, s[44:45]
	v_mov_b32_e32 v176, s93
	v_lshrrev_b32_e32 v176, 10, v176
	v_mul_u32_u24_e32 v176, 0x900, v176
	v_add_u32_e32 v176, 0x22000, v176
	v_and_b32_e32 v175, 15, v1
	v_lshl_add_u32 v175, v175, 2, v176
	v_and_b32_e32 v177, 0x18, v229
	v_lshl_add_u32 v176, v177, 2, v176
	ds_read_b128 v[138:141], v176 offset:528
	ds_read_b128 v[142:145], v176 offset:512
	ds_read_b128 v[130:133], v176 offset:656
	s_nop 0
	ds_read_b128 v[134:137], v176 offset:640
	s_nop 0
	ds_read_b32 v147, v175
	ds_read_b32 v161, v175 offset:64
	ds_read_b32 v166, v175 offset:128
	ds_read_b32 v160, v175 offset:192
	ds_read_b32 v159, v175 offset:256
	ds_read_b32 v158, v175 offset:320
	ds_read_b32 v155, v175 offset:384
	s_nop 0
	ds_read_b32 v151, v175 offset:448
	s_cselect_b64 vcc, -1, 0
	v_mov_b32_e32 v149, s1
	s_movk_i32 s17, 0xc00
	v_cndmask_b32_e32 v150, 1.0, v149, vcc
	s_waitcnt lgkmcnt(0)
	v_fmamk_f32 v147, v147, 0x3a800000, v213
	v_rsq_f32_e32 v154, v147
	v_mad_u64_u32 v[152:153], s[44:45], v148, s17, v[146:147]
	v_mov_b32_e32 v153, v0
	v_pk_fma_f32 v[146:147], v[126:127], v[154:155], v[142:143] op_sel_hi:[1,0,1]
	v_pk_fma_f32 v[148:149], v[128:129], v[154:155], v[144:145] op_sel_hi:[1,0,1]
	v_pk_fma_f32 v[156:157], v[122:123], v[154:155], v[138:139] op_sel_hi:[1,0,1]
	v_pk_mul_f32 v[148:149], v[150:151], v[148:149] op_sel_hi:[0,1]
	v_pk_mul_f32 v[146:147], v[150:151], v[146:147] op_sel_hi:[0,1]
	v_pk_mul_f32 v[156:157], v[150:151], v[156:157] op_sel_hi:[0,1]
	v_pk_fma_f32 v[162:163], v[124:125], v[154:155], v[140:141] op_sel_hi:[1,0,1]
	v_cvt_pk_bf16_f32 v146, v146, v147
	v_cvt_pk_bf16_f32 v147, v148, v149
	v_cvt_pk_bf16_f32 v148, v156, v157
	v_lshl_add_u64 v[156:157], v[152:153], 1, s[42:43]
	v_pk_mul_f32 v[162:163], v[150:151], v[162:163] op_sel_hi:[0,1]
	v_cvt_pk_bf16_f32 v149, v162, v163
	global_store_dwordx4 v[156:157], v[146:149], off
	v_pk_fma_f32 v[162:163], v[114:115], v[154:155], v[130:131] op_sel_hi:[1,0,1]
	v_pk_fma_f32 v[164:165], v[116:117], v[154:155], v[132:133] op_sel_hi:[1,0,1]
	v_pk_fma_f32 v[146:147], v[118:119], v[154:155], v[134:135] op_sel_hi:[1,0,1]
	v_pk_fma_f32 v[148:149], v[120:121], v[154:155], v[136:137] op_sel_hi:[1,0,1]
	v_pk_mul_f32 v[146:147], v[150:151], v[146:147] op_sel_hi:[0,1]
	v_pk_mul_f32 v[148:149], v[150:151], v[148:149] op_sel_hi:[0,1]
	v_cvt_pk_bf16_f32 v146, v146, v147
	v_pk_mul_f32 v[164:165], v[150:151], v[164:165] op_sel_hi:[0,1]
	v_pk_mul_f32 v[162:163], v[150:151], v[162:163] op_sel_hi:[0,1]
	v_cvt_pk_bf16_f32 v147, v148, v149
	v_cvt_pk_bf16_f32 v148, v162, v163
	v_cvt_pk_bf16_f32 v149, v164, v165
	global_store_dwordx4 v[156:157], v[146:149], off offset:256
	v_add_u32_e32 v156, 0xc000, v152
	v_mov_b32_e32 v157, v0
	v_fmamk_f32 v146, v161, 0x3a800000, v213
	v_rsq_f32_e32 v154, v146
	v_lshl_add_u64 v[156:157], v[156:157], 1, s[42:43]
	v_pk_fma_f32 v[146:147], v[110:111], v[154:155], v[142:143] op_sel_hi:[1,0,1]
	v_pk_fma_f32 v[148:149], v[112:113], v[154:155], v[144:145] op_sel_hi:[1,0,1]
	v_pk_mul_f32 v[146:147], v[150:151], v[146:147] op_sel_hi:[0,1]
	v_pk_mul_f32 v[148:149], v[150:151], v[148:149] op_sel_hi:[0,1]
	v_pk_fma_f32 v[162:163], v[102:103], v[154:155], v[138:139] op_sel_hi:[1,0,1]
	v_pk_fma_f32 v[164:165], v[104:105], v[154:155], v[140:141] op_sel_hi:[1,0,1]
	v_cvt_pk_bf16_f32 v146, v146, v147
	v_cvt_pk_bf16_f32 v147, v148, v149
	v_pk_mul_f32 v[162:163], v[150:151], v[162:163] op_sel_hi:[0,1]
	v_pk_mul_f32 v[164:165], v[150:151], v[164:165] op_sel_hi:[0,1]
	v_cvt_pk_bf16_f32 v148, v162, v163
	v_cvt_pk_bf16_f32 v149, v164, v165
	global_store_dwordx4 v[156:157], v[146:149], off
	v_pk_fma_f32 v[162:163], v[98:99], v[154:155], v[130:131] op_sel_hi:[1,0,1]
	v_pk_fma_f32 v[164:165], v[100:101], v[154:155], v[132:133] op_sel_hi:[1,0,1]
	v_pk_fma_f32 v[146:147], v[106:107], v[154:155], v[134:135] op_sel_hi:[1,0,1]
	v_pk_fma_f32 v[148:149], v[108:109], v[154:155], v[136:137] op_sel_hi:[1,0,1]
	v_pk_mul_f32 v[146:147], v[150:151], v[146:147] op_sel_hi:[0,1]
	v_pk_mul_f32 v[148:149], v[150:151], v[148:149] op_sel_hi:[0,1]
	v_cvt_pk_bf16_f32 v146, v146, v147
	v_pk_mul_f32 v[164:165], v[150:151], v[164:165] op_sel_hi:[0,1]
	v_pk_mul_f32 v[162:163], v[150:151], v[162:163] op_sel_hi:[0,1]
	v_cvt_pk_bf16_f32 v147, v148, v149
	v_cvt_pk_bf16_f32 v148, v162, v163
	v_cvt_pk_bf16_f32 v149, v164, v165
	global_store_dwordx4 v[156:157], v[146:149], off offset:256
	s_nop 1
	v_fmamk_f32 v146, v166, 0x3a800000, v213
	v_rsq_f32_e32 v146, v146
	v_add_u32_e32 v148, 0x18000, v152
	v_mov_b32_e32 v149, v0
	v_pk_fma_f32 v[156:157], v[94:95], v[146:147], v[142:143] op_sel_hi:[1,0,1]
	v_pk_fma_f32 v[162:163], v[96:97], v[146:147], v[144:145] op_sel_hi:[1,0,1]
	v_pk_mul_f32 v[156:157], v[150:151], v[156:157] op_sel_hi:[0,1]
	v_pk_mul_f32 v[164:165], v[150:151], v[162:163] op_sel_hi:[0,1]
	v_pk_fma_f32 v[162:163], v[86:87], v[146:147], v[138:139] op_sel_hi:[1,0,1]
	v_pk_fma_f32 v[166:167], v[88:89], v[146:147], v[140:141] op_sel_hi:[1,0,1]
	v_pk_mul_f32 v[168:169], v[150:151], v[162:163] op_sel_hi:[0,1]
	v_pk_mul_f32 v[166:167], v[150:151], v[166:167] op_sel_hi:[0,1]
	v_cvt_pk_bf16_f32 v162, v156, v157
	v_cvt_pk_bf16_f32 v163, v164, v165
	v_cvt_pk_bf16_f32 v164, v168, v169
	v_cvt_pk_bf16_f32 v165, v166, v167
	v_lshl_add_u64 v[156:157], v[148:149], 1, s[42:43]
; __device__ __forceinline__ unsigned cvt_pk_bf16(float lo, float hi) { unsigned r; asm volatile("v_cvt_pk_bf16_f32 %0, %1, %2" : "=v"(r) : "v"(lo), "v"(hi)); return r; }
;     __device__ __forceinline__ void operator()(const f32x4 (&acc)[2][2][4][2], const Unit& u, int wr, int wc, int fr, int fq) const {
;     ...
;         for (int ai = 0; ai < 2; ++ai)
; #pragma unroll
;             for (int m = 0; m < 4; ++m) {
;                 const int row = row0 + ai * HALF + m * 16;
;                 const float rs = __builtin_amdgcn_rsqf(sq[ai][m] * (1.0f / 1024.0f) + RMS_EPS_F);
; #pragma unroll
;                 for (int bj = 0; bj < 2; ++bj) {
;                     const f32x4 v0 = (acc[ai][bj][m][0] * rs + bv[bj][0]) * sc, v1 = (acc[ai][bj][m][1] * rs + bv[bj][1]) * sc;
;                     u32x4 w; w.x = cvt_pk_bf16(v0[0], v0[1]); w.y = cvt_pk_bf16(v0[2], v0[3]); w.z = cvt_pk_bf16(v1[0], v1[1]); w.w = cvt_pk_bf16(v1[2], v1[3]);
;                     *(u32x4*)(O + ((unsigned)row * 3072u + (unsigned)(col0 + bj * HALF))) = w;
;                 }
	global_store_dwordx4 v[156:157], v[162:165], off
	v_pk_fma_f32 v[148:149], v[90:91], v[146:147], v[134:135] op_sel_hi:[1,0,1]
	s_nop 0
	v_pk_fma_f32 v[162:163], v[92:93], v[146:147], v[136:137] op_sel_hi:[1,0,1]
	v_pk_fma_f32 v[164:165], v[82:83], v[146:147], v[130:131] op_sel_hi:[1,0,1]
	v_pk_fma_f32 v[146:147], v[84:85], v[146:147], v[132:133] op_sel_hi:[1,0,1]
	v_pk_mul_f32 v[148:149], v[150:151], v[148:149] op_sel_hi:[0,1]
	v_pk_mul_f32 v[166:167], v[150:151], v[146:147] op_sel_hi:[0,1]
	v_cvt_pk_bf16_f32 v146, v148, v149
	v_pk_mul_f32 v[162:163], v[150:151], v[162:163] op_sel_hi:[0,1]
	v_pk_mul_f32 v[164:165], v[150:151], v[164:165] op_sel_hi:[0,1]
	v_cvt_pk_bf16_f32 v147, v162, v163
	v_cvt_pk_bf16_f32 v148, v164, v165
	v_cvt_pk_bf16_f32 v149, v166, v167
	global_store_dwordx4 v[156:157], v[146:149], off offset:256
	v_add_u32_e32 v156, 0x24000, v152
	v_mov_b32_e32 v157, v0
	v_fmamk_f32 v146, v160, 0x3a800000, v213
	v_rsq_f32_e32 v154, v146
	v_lshl_add_u64 v[156:157], v[156:157], 1, s[42:43]
	v_pk_fma_f32 v[146:147], v[78:79], v[154:155], v[142:143] op_sel_hi:[1,0,1]
	v_pk_fma_f32 v[148:149], v[80:81], v[154:155], v[144:145] op_sel_hi:[1,0,1]
	v_pk_mul_f32 v[146:147], v[150:151], v[146:147] op_sel_hi:[0,1]
	v_pk_mul_f32 v[148:149], v[150:151], v[148:149] op_sel_hi:[0,1]
	v_pk_fma_f32 v[160:161], v[70:71], v[154:155], v[138:139] op_sel_hi:[1,0,1]
	v_pk_fma_f32 v[162:163], v[72:73], v[154:155], v[140:141] op_sel_hi:[1,0,1]
	v_cvt_pk_bf16_f32 v146, v146, v147
	v_cvt_pk_bf16_f32 v147, v148, v149
	v_pk_mul_f32 v[160:161], v[150:151], v[160:161] op_sel_hi:[0,1]
	v_pk_mul_f32 v[162:163], v[150:151], v[162:163] op_sel_hi:[0,1]
	v_cvt_pk_bf16_f32 v148, v160, v161
	v_cvt_pk_bf16_f32 v149, v162, v163
	global_store_dwordx4 v[156:157], v[146:149], off
	v_pk_fma_f32 v[160:161], v[66:67], v[154:155], v[130:131] op_sel_hi:[1,0,1]
	v_pk_fma_f32 v[162:163], v[68:69], v[154:155], v[132:133] op_sel_hi:[1,0,1]
	v_pk_fma_f32 v[146:147], v[74:75], v[154:155], v[134:135] op_sel_hi:[1,0,1]
	v_pk_fma_f32 v[148:149], v[76:77], v[154:155], v[136:137] op_sel_hi:[1,0,1]
	v_pk_mul_f32 v[146:147], v[150:151], v[146:147] op_sel_hi:[0,1]
	v_pk_mul_f32 v[148:149], v[150:151], v[148:149] op_sel_hi:[0,1]
	v_cvt_pk_bf16_f32 v146, v146, v147
	v_pk_mul_f32 v[162:163], v[150:151], v[162:163] op_sel_hi:[0,1]
	v_pk_mul_f32 v[160:161], v[150:151], v[160:161] op_sel_hi:[0,1]
	v_cvt_pk_bf16_f32 v147, v148, v149
	v_cvt_pk_bf16_f32 v148, v160, v161
	v_cvt_pk_bf16_f32 v149, v162, v163
	global_store_dwordx4 v[156:157], v[146:149], off offset:256
	v_add_u32_e32 v156, 0x60000, v152
	v_mov_b32_e32 v157, v0
	v_fmamk_f32 v146, v159, 0x3a800000, v213
	v_rsq_f32_e32 v154, v146
	v_lshl_add_u64 v[156:157], v[156:157], 1, s[42:43]
	v_pk_fma_f32 v[146:147], v[62:63], v[154:155], v[142:143] op_sel_hi:[1,0,1]
	v_pk_fma_f32 v[148:149], v[64:65], v[154:155], v[144:145] op_sel_hi:[1,0,1]
	v_pk_mul_f32 v[146:147], v[150:151], v[146:147] op_sel_hi:[0,1]
	v_pk_mul_f32 v[148:149], v[150:151], v[148:149] op_sel_hi:[0,1]
	v_pk_fma_f32 v[160:161], v[54:55], v[154:155], v[138:139] op_sel_hi:[1,0,1]
	v_pk_fma_f32 v[162:163], v[56:57], v[154:155], v[140:141] op_sel_hi:[1,0,1]
	v_cvt_pk_bf16_f32 v146, v146, v147
	v_cvt_pk_bf16_f32 v147, v148, v149
	v_pk_mul_f32 v[160:161], v[150:151], v[160:161] op_sel_hi:[0,1]
	v_pk_mul_f32 v[162:163], v[150:151], v[162:163] op_sel_hi:[0,1]
	v_cvt_pk_bf16_f32 v148, v160, v161
	v_cvt_pk_bf16_f32 v149, v162, v163
	global_store_dwordx4 v[156:157], v[146:149], off
	v_pk_fma_f32 v[160:161], v[50:51], v[154:155], v[130:131] op_sel_hi:[1,0,1]
	v_pk_fma_f32 v[162:163], v[52:53], v[154:155], v[132:133] op_sel_hi:[1,0,1]
	v_pk_fma_f32 v[146:147], v[58:59], v[154:155], v[134:135] op_sel_hi:[1,0,1]
	v_pk_fma_f32 v[148:149], v[60:61], v[154:155], v[136:137] op_sel_hi:[1,0,1]
	v_pk_mul_f32 v[146:147], v[150:151], v[146:147] op_sel_hi:[0,1]
	v_pk_mul_f32 v[148:149], v[150:151], v[148:149] op_sel_hi:[0,1]
	v_cvt_pk_bf16_f32 v146, v146, v147
	v_pk_mul_f32 v[162:163], v[150:151], v[162:163] op_sel_hi:[0,1]
	v_pk_mul_f32 v[160:161], v[150:151], v[160:161] op_sel_hi:[0,1]
	v_cvt_pk_bf16_f32 v147, v148, v149
	v_cvt_pk_bf16_f32 v148, v160, v161
	v_cvt_pk_bf16_f32 v149, v162, v163
	global_store_dwordx4 v[156:157], v[146:149], off offset:256
	v_add_u32_e32 v156, 0x6c000, v152
	v_mov_b32_e32 v157, v0
	v_fmamk_f32 v146, v158, 0x3a800000, v213
	v_rsq_f32_e32 v154, v146
	v_lshl_add_u64 v[156:157], v[156:157], 1, s[42:43]
	v_pk_fma_f32 v[146:147], v[46:47], v[154:155], v[142:143] op_sel_hi:[1,0,1]
	v_pk_fma_f32 v[148:149], v[48:49], v[154:155], v[144:145] op_sel_hi:[1,0,1]
	v_pk_mul_f32 v[146:147], v[150:151], v[146:147] op_sel_hi:[0,1]
	v_pk_mul_f32 v[148:149], v[150:151], v[148:149] op_sel_hi:[0,1]
; __device__ __forceinline__ unsigned cvt_pk_bf16(float lo, float hi) { unsigned r; asm volatile("v_cvt_pk_bf16_f32 %0, %1, %2" : "=v"(r) : "v"(lo), "v"(hi)); return r; }
;     __device__ __forceinline__ void operator()(const f32x4 (&acc)[2][2][4][2], const Unit& u, int wr, int wc, int fr, int fq) const {
;     ...
;         for (int ai = 0; ai < 2; ++ai)
; #pragma unroll
;             for (int m = 0; m < 4; ++m) {
;                 const int row = row0 + ai * HALF + m * 16;
;                 const float rs = __builtin_amdgcn_rsqf(sq[ai][m] * (1.0f / 1024.0f) + RMS_EPS_F);
; #pragma unroll
;                 for (int bj = 0; bj < 2; ++bj) {
;                     const f32x4 v0 = (acc[ai][bj][m][0] * rs + bv[bj][0]) * sc, v1 = (acc[ai][bj][m][1] * rs + bv[bj][1]) * sc;
;                     u32x4 w; w.x = cvt_pk_bf16(v0[0], v0[1]); w.y = cvt_pk_bf16(v0[2], v0[3]); w.z = cvt_pk_bf16(v1[0], v1[1]); w.w = cvt_pk_bf16(v1[2], v1[3]);
;                     *(u32x4*)(O + ((unsigned)row * 3072u + (unsigned)(col0 + bj * HALF))) = w;
;                 }
	v_pk_fma_f32 v[158:159], v[38:39], v[154:155], v[138:139] op_sel_hi:[1,0,1]
	v_pk_fma_f32 v[160:161], v[40:41], v[154:155], v[140:141] op_sel_hi:[1,0,1]
	v_cvt_pk_bf16_f32 v146, v146, v147
	v_cvt_pk_bf16_f32 v147, v148, v149
	v_pk_mul_f32 v[158:159], v[150:151], v[158:159] op_sel_hi:[0,1]
	v_pk_mul_f32 v[160:161], v[150:151], v[160:161] op_sel_hi:[0,1]
	v_cvt_pk_bf16_f32 v148, v158, v159
	v_cvt_pk_bf16_f32 v149, v160, v161
	global_store_dwordx4 v[156:157], v[146:149], off
	v_pk_fma_f32 v[158:159], v[34:35], v[154:155], v[130:131] op_sel_hi:[1,0,1]
	v_pk_fma_f32 v[160:161], v[36:37], v[154:155], v[132:133] op_sel_hi:[1,0,1]
	v_pk_fma_f32 v[146:147], v[42:43], v[154:155], v[134:135] op_sel_hi:[1,0,1]
	v_pk_fma_f32 v[148:149], v[44:45], v[154:155], v[136:137] op_sel_hi:[1,0,1]
	v_pk_mul_f32 v[146:147], v[150:151], v[146:147] op_sel_hi:[0,1]
	v_pk_mul_f32 v[148:149], v[150:151], v[148:149] op_sel_hi:[0,1]
	v_cvt_pk_bf16_f32 v146, v146, v147
	v_pk_mul_f32 v[160:161], v[150:151], v[160:161] op_sel_hi:[0,1]
	v_pk_mul_f32 v[158:159], v[150:151], v[158:159] op_sel_hi:[0,1]
	v_cvt_pk_bf16_f32 v147, v148, v149
	v_cvt_pk_bf16_f32 v148, v158, v159
	v_cvt_pk_bf16_f32 v149, v160, v161
	global_store_dwordx4 v[156:157], v[146:149], off offset:256
	v_add_u32_e32 v156, 0x78000, v152
	v_mov_b32_e32 v157, v0
	v_fmamk_f32 v146, v155, 0x3a800000, v213
	v_rsq_f32_e32 v154, v146
	v_lshl_add_u64 v[156:157], v[156:157], 1, s[42:43]
	v_pk_fma_f32 v[146:147], v[30:31], v[154:155], v[142:143] op_sel_hi:[1,0,1]
	v_pk_fma_f32 v[148:149], v[32:33], v[154:155], v[144:145] op_sel_hi:[1,0,1]
	v_pk_mul_f32 v[146:147], v[150:151], v[146:147] op_sel_hi:[0,1]
	v_pk_mul_f32 v[148:149], v[150:151], v[148:149] op_sel_hi:[0,1]
	v_pk_fma_f32 v[158:159], v[22:23], v[154:155], v[138:139] op_sel_hi:[1,0,1]
	v_pk_fma_f32 v[160:161], v[24:25], v[154:155], v[140:141] op_sel_hi:[1,0,1]
	v_cvt_pk_bf16_f32 v146, v146, v147
	v_cvt_pk_bf16_f32 v147, v148, v149
	v_pk_mul_f32 v[158:159], v[150:151], v[158:159] op_sel_hi:[0,1]
	v_pk_mul_f32 v[160:161], v[150:151], v[160:161] op_sel_hi:[0,1]
	v_cvt_pk_bf16_f32 v148, v158, v159
	v_cvt_pk_bf16_f32 v149, v160, v161
	global_store_dwordx4 v[156:157], v[146:149], off
	v_pk_fma_f32 v[158:159], v[18:19], v[154:155], v[130:131] op_sel_hi:[1,0,1]
	s_nop 0
	v_pk_fma_f32 v[146:147], v[26:27], v[154:155], v[134:135] op_sel_hi:[1,0,1]
	v_pk_fma_f32 v[148:149], v[28:29], v[154:155], v[136:137] op_sel_hi:[1,0,1]
	v_pk_mul_f32 v[146:147], v[150:151], v[146:147] op_sel_hi:[0,1]
	v_pk_mul_f32 v[148:149], v[150:151], v[148:149] op_sel_hi:[0,1]
	v_pk_fma_f32 v[154:155], v[20:21], v[154:155], v[132:133] op_sel_hi:[1,0,1]
	v_cvt_pk_bf16_f32 v146, v146, v147
	v_pk_mul_f32 v[158:159], v[150:151], v[158:159] op_sel_hi:[0,1]
	v_pk_mul_f32 v[154:155], v[150:151], v[154:155] op_sel_hi:[0,1]
	v_cvt_pk_bf16_f32 v147, v148, v149
	v_cvt_pk_bf16_f32 v148, v158, v159
	v_cvt_pk_bf16_f32 v149, v154, v155
	global_store_dwordx4 v[156:157], v[146:149], off offset:256
	s_nop 1
	v_fmamk_f32 v146, v151, 0x3a800000, v213
	v_rsq_f32_e32 v146, v146
	v_add_u32_e32 v148, 0x84000, v152
	v_mov_b32_e32 v149, v0
	v_pk_fma_f32 v[142:143], v[14:15], v[146:147], v[142:143] op_sel_hi:[1,0,1]
	v_pk_fma_f32 v[144:145], v[16:17], v[146:147], v[144:145] op_sel_hi:[1,0,1]
	v_pk_mul_f32 v[142:143], v[150:151], v[142:143] op_sel_hi:[0,1]
	v_pk_fma_f32 v[138:139], v[6:7], v[146:147], v[138:139] op_sel_hi:[1,0,1]
	v_pk_fma_f32 v[140:141], v[8:9], v[146:147], v[140:141] op_sel_hi:[1,0,1]
	v_pk_mul_f32 v[144:145], v[150:151], v[144:145] op_sel_hi:[0,1]
	v_pk_mul_f32 v[152:153], v[150:151], v[140:141] op_sel_hi:[0,1]
	v_pk_mul_f32 v[140:141], v[150:151], v[138:139] op_sel_hi:[0,1]
	v_cvt_pk_bf16_f32 v138, v142, v143
	v_cvt_pk_bf16_f32 v139, v144, v145
	v_lshl_add_u64 v[142:143], v[148:149], 1, s[42:43]
	v_pk_fma_f32 v[130:131], v[2:3], v[146:147], v[130:131] op_sel_hi:[1,0,1]
	v_pk_fma_f32 v[132:133], v[4:5], v[146:147], v[132:133] op_sel_hi:[1,0,1]
	v_cvt_pk_bf16_f32 v140, v140, v141
	v_cvt_pk_bf16_f32 v141, v152, v153
	global_store_dwordx4 v[142:143], v[138:141], off
	v_pk_fma_f32 v[134:135], v[10:11], v[146:147], v[134:135] op_sel_hi:[1,0,1]
	v_pk_fma_f32 v[136:137], v[12:13], v[146:147], v[136:137] op_sel_hi:[1,0,1]
	v_pk_mul_f32 v[138:139], v[150:151], v[132:133] op_sel_hi:[0,1]
	v_pk_mul_f32 v[132:133], v[150:151], v[130:131] op_sel_hi:[0,1]
	v_pk_mul_f32 v[136:137], v[150:151], v[136:137] op_sel_hi:[0,1]
	v_pk_mul_f32 v[134:135], v[150:151], v[134:135] op_sel_hi:[0,1]
	v_cvt_pk_bf16_f32 v130, v134, v135
	v_cvt_pk_bf16_f32 v131, v136, v137
	v_cvt_pk_bf16_f32 v132, v132, v133
	v_cvt_pk_bf16_f32 v133, v138, v139
	global_store_dwordx4 v[142:143], v[130:133], off offset:256

;     __device__ __forceinline__ void operator()(const f32x4 (&acc)[2][2][4][2], const Unit& u, int wr, int wc, int fr, int fq) const {
;         const float* cb = (u.pm >= 64) ? cb_ctx : cb_lat;
;         const int row0 = u.pm * BM + wr * 64 + fr, bcol0 = u.pn * BM + wc * 32 + 8 * fq, ocol = u.pn * HALF + wc * 32 + 8 * fq;
;         constexpr float NL2E = -1.44269504f;
;         f32x2 b0[4], b1[4], bz[4];
; #pragma unroll
;         for (int n = 0; n < 2; ++n) { const f32x4 x0 = *(const f32x4*)(cb + bcol0 + 4 * n), x1 = *(const f32x4*)(cb + bcol0 + HALF + 4 * n);
;             b0[2 * n] = (f32x2){x0[0], x0[1]}; b0[2 * n + 1] = (f32x2){x0[2], x0[3]}; b1[2 * n] = (f32x2){x1[0], x1[1]}; b1[2 * n + 1] = (f32x2){x1[2], x1[3]}; }
; #pragma unroll
;         for (int p = 0; p < 4; ++p) bz[p] = (MODE == 0 ? b0[p] : b1[p]) * NL2E;
;         float sq[2][4];
; #pragma unroll
;         for (int ai = 0; ai < 2; ++ai)
; #pragma unroll
;             for (int m = 0; m < 4; ++m) sq[ai][m] = ssq[row0 + ai * HALF + m * 16];
; #pragma unroll
;         for (int ai = 0; ai < 2; ++ai)
; #pragma unroll
;             for (int m = 0; m < 4; ++m) {
;                 const int row = row0 + ai * HALF + m * 16;
;                 const float rs = __builtin_amdgcn_rsqf(sq[ai][m] * (1.0f / 1024.0f) + RMS_EPS_F), rz = rs * NL2E;
;                 unsigned w[4];
; #pragma unroll
;                 for (int p = 0; p < 4; ++p) {
;                     const f32x4 a0 = acc[ai][0][m][p >> 1], a1 = acc[ai][1][m][p >> 1];
;                     const f32x2 c0 = (p & 1) ? (f32x2){a0[2], a0[3]} : (f32x2){a0[0], a0[1]}, c1 = (p & 1) ? (f32x2){a1[2], a1[3]} : (f32x2){a1[0], a1[1]};
;                     const f32x2 v0 = c0 * rs + b0[p], v1 = c1 * rs + b1[p];
;                     const f32x2 t = (MODE == 0 ? c0 : c1) * rz + bz[p];
;                     f32x2 d; d.x = __builtin_amdgcn_exp2f(t.x); d.y = __builtin_amdgcn_exp2f(t.y); d = d + 1.0f;
;                     f32x2 r; r.x = __builtin_amdgcn_rcpf(d.x); r.y = __builtin_amdgcn_rcpf(d.y);
;                     const f32x2 o = (MODE == 0) ? (v0 * v1) * r : v0 * r;
;                     w[p] = cvt_pk_bf16(o.x, o.y);
;                 }
;                 u32x4 wv; wv.x = w[0]; wv.y = w[1]; wv.z = w[2]; wv.w = w[3];
;                 *(u32x4*)(O + ((unsigned)row * (unsigned)ldc + (unsigned)ocol)) = wv;
.LBB0_507:
	s_cmp_eq_u32 s0, 1
	s_mov_b64 s[42:43], -1
	s_cbranch_scc1 .LBB0_509
	s_mov_b64 s[44:45], s[72:73]
	s_mov_b64 s[60:61], s[56:57]
	s_mov_b64 s[42:43], s[24:25]
	s_mov_b64 s[64:65], s[76:77]
	s_cmp_gt_i32 s14, 63
	s_cselect_b32 s17, s61, s65
	s_cselect_b32 s60, s60, s64
	v_lshl_or_b32 v132, s15, 8, v229
	v_lshl_add_u32 v158, s14, 8, v1
	v_mov_b32_e32 v130, s60
	v_mov_b32_e32 v131, s17
	v_ashrrev_i32_e32 v133, 31, v132
	v_ashrrev_i32_e32 v159, 31, v158
	v_lshl_add_u64 v[142:143], v[132:133], 2, v[130:131]
	v_lshl_add_u64 v[146:147], v[158:159], 2, s[44:45]
	v_mov_b32_e32 v176, s93
	v_lshrrev_b32_e32 v176, 10, v176
	v_mul_u32_u24_e32 v176, 0x900, v176
	v_add_u32_e32 v176, 0x22000, v176
	v_and_b32_e32 v175, 15, v1
	v_lshl_add_u32 v175, v175, 2, v176
	v_and_b32_e32 v177, 0x18, v229
	v_lshl_add_u32 v176, v177, 2, v176
	ds_read_b128 v[130:133], v176 offset:528
	ds_read_b128 v[138:141], v176 offset:512
	ds_read_b128 v[134:137], v176 offset:656
	s_nop 0
	ds_read_b128 v[142:145], v176 offset:640
	s_nop 0
	ds_read_b32 v148, v175
	ds_read_b32 v174, v175 offset:64
	ds_read_b32 v167, v175 offset:128
	ds_read_b32 v166, v175 offset:192
	ds_read_b32 v165, v175 offset:256
	ds_read_b32 v164, v175 offset:320
	ds_read_b32 v163, v175 offset:384
	ds_read_b32 v161, v175 offset:448
	v_lshl_or_b32 v160, s15, 7, v229
	s_mul_i32 s17, s90, 0x50
	s_waitcnt lgkmcnt(0)
	v_fmamk_f32 v146, v148, 0x3a800000, v213
	v_rsq_f32_e32 v162, v146
	v_pk_mul_f32 v[152:153], v[130:131], s[30:31] op_sel_hi:[1,0]
	v_pk_mul_f32 v[156:157], v[138:139], s[30:31] op_sel_hi:[1,0]
	v_mul_f32_e32 v168, 0xbfb8aa3b, v162
	v_pk_fma_f32 v[170:171], v[126:127], v[168:169], v[156:157] op_sel_hi:[1,0,1]
	v_pk_mul_f32 v[154:155], v[140:141], s[30:31] op_sel_hi:[1,0]
	v_exp_f32_e32 v170, v170
	v_exp_f32_e32 v171, v171
	v_pk_fma_f32 v[172:173], v[128:129], v[168:169], v[154:155] op_sel_hi:[1,0,1]
	v_pk_fma_f32 v[146:147], v[126:127], v[162:163], v[138:139] op_sel_hi:[1,0,1]
	v_exp_f32_e32 v172, v172
	v_exp_f32_e32 v173, v173
	v_pk_add_f32 v[170:171], v[170:171], 1.0 op_sel_hi:[1,0]
	v_pk_fma_f32 v[148:149], v[118:119], v[162:163], v[142:143] op_sel_hi:[1,0,1]
	v_rcp_f32_e32 v170, v170
	v_rcp_f32_e32 v171, v171
	v_pk_add_f32 v[172:173], v[172:173], 1.0 op_sel_hi:[1,0]
	v_pk_mul_f32 v[146:147], v[146:147], v[148:149]
	v_rcp_f32_e32 v172, v172
	v_rcp_f32_e32 v173, v173
	v_pk_mul_f32 v[146:147], v[146:147], v[170:171]
	v_pk_fma_f32 v[148:149], v[128:129], v[162:163], v[140:141] op_sel_hi:[1,0,1]
	v_pk_fma_f32 v[170:171], v[120:121], v[162:163], v[144:145] op_sel_hi:[1,0,1]
	v_pk_mul_f32 v[150:151], v[132:133], s[30:31] op_sel_hi:[1,0]
	v_pk_mul_f32 v[148:149], v[148:149], v[170:171]
	v_cvt_pk_bf16_f32 v146, v146, v147
	v_pk_fma_f32 v[170:171], v[114:115], v[162:163], v[134:135] op_sel_hi:[1,0,1]
	v_pk_mul_f32 v[148:149], v[148:149], v[172:173]
	v_pk_fma_f32 v[172:173], v[122:123], v[168:169], v[152:153] op_sel_hi:[1,0,1]
	v_pk_fma_f32 v[168:169], v[124:125], v[168:169], v[150:151] op_sel_hi:[1,0,1]
	v_exp_f32_e32 v172, v172
	v_exp_f32_e32 v173, v173
	v_exp_f32_e32 v168, v168
	v_exp_f32_e32 v169, v169
	v_cvt_pk_bf16_f32 v147, v148, v149
	v_pk_add_f32 v[172:173], v[172:173], 1.0 op_sel_hi:[1,0]
	v_pk_fma_f32 v[148:149], v[122:123], v[162:163], v[130:131] op_sel_hi:[1,0,1]
	v_rcp_f32_e32 v172, v172
	v_rcp_f32_e32 v173, v173
	v_pk_add_f32 v[168:169], v[168:169], 1.0 op_sel_hi:[1,0]
	v_pk_mul_f32 v[148:149], v[148:149], v[170:171]
	v_rcp_f32_e32 v168, v168
	v_rcp_f32_e32 v169, v169
	v_pk_mul_f32 v[148:149], v[148:149], v[172:173]
	v_pk_fma_f32 v[170:171], v[124:125], v[162:163], v[132:133] op_sel_hi:[1,0,1]
	v_pk_fma_f32 v[172:173], v[116:117], v[162:163], v[136:137] op_sel_hi:[1,0,1]
	v_mad_u64_u32 v[158:159], s[44:45], v158, s90, v[160:161]
	v_pk_mul_f32 v[170:171], v[170:171], v[172:173]
	v_mov_b32_e32 v159, v0
	v_pk_mul_f32 v[168:169], v[170:171], v[168:169]
	v_cvt_pk_bf16_f32 v148, v148, v149
	s_nop 0
	v_cvt_pk_bf16_f32 v149, v168, v169
	v_lshl_add_u64 v[168:169], v[158:159], 1, s[42:43]
	global_store_dwordx4 v[168:169], v[146:149], off
	v_add_u32_e32 v158, s12, v158
	s_nop 0
	v_fmamk_f32 v146, v174, 0x3a800000, v213
	v_rsq_f32_e32 v160, v146
	s_nop 0
	v_mul_f32_e32 v162, 0xbfb8aa3b, v160
	v_pk_fma_f32 v[168:169], v[110:111], v[162:163], v[156:157] op_sel_hi:[1,0,1]
	v_pk_fma_f32 v[170:171], v[112:113], v[162:163], v[154:155] op_sel_hi:[1,0,1]
	v_exp_f32_e32 v168, v168
	v_exp_f32_e32 v169, v169
	v_exp_f32_e32 v170, v170
	v_exp_f32_e32 v171, v171
	v_pk_fma_f32 v[146:147], v[110:111], v[160:161], v[138:139] op_sel_hi:[1,0,1]
	v_pk_add_f32 v[168:169], v[168:169], 1.0 op_sel_hi:[1,0]
	v_pk_fma_f32 v[148:149], v[106:107], v[160:161], v[142:143] op_sel_hi:[1,0,1]
	v_rcp_f32_e32 v168, v168
	v_rcp_f32_e32 v169, v169
	v_pk_add_f32 v[170:171], v[170:171], 1.0 op_sel_hi:[1,0]
	v_pk_mul_f32 v[146:147], v[146:147], v[148:149]
	v_rcp_f32_e32 v170, v170
	v_rcp_f32_e32 v171, v171
	v_pk_mul_f32 v[146:147], v[146:147], v[168:169]
	v_pk_fma_f32 v[148:149], v[112:113], v[160:161], v[140:141] op_sel_hi:[1,0,1]
	v_pk_fma_f32 v[168:169], v[108:109], v[160:161], v[144:145] op_sel_hi:[1,0,1]
	v_pk_fma_f32 v[172:173], v[104:105], v[162:163], v[150:151] op_sel_hi:[1,0,1]
	v_pk_mul_f32 v[148:149], v[148:149], v[168:169]
	v_exp_f32_e32 v172, v172
	v_pk_mul_f32 v[148:149], v[148:149], v[170:171]
	v_pk_fma_f32 v[170:171], v[102:103], v[162:163], v[152:153] op_sel_hi:[1,0,1]
	v_exp_f32_e32 v173, v173
	v_exp_f32_e32 v170, v170
	v_exp_f32_e32 v171, v171
	v_cvt_pk_bf16_f32 v146, v146, v147
	v_pk_add_f32 v[172:173], v[172:173], 1.0 op_sel_hi:[1,0]
	v_cvt_pk_bf16_f32 v147, v148, v149
	v_pk_add_f32 v[170:171], v[170:171], 1.0 op_sel_hi:[1,0]
; __device__ __forceinline__ unsigned cvt_pk_bf16(float lo, float hi) { unsigned r; asm volatile("v_cvt_pk_bf16_f32 %0, %1, %2" : "=v"(r) : "v"(lo), "v"(hi)); return r; }
;     __device__ __forceinline__ void operator()(const f32x4 (&acc)[2][2][4][2], const Unit& u, int wr, int wc, int fr, int fq) const {
;     ...
;             for (int m = 0; m < 4; ++m) {
;                 const int row = row0 + ai * HALF + m * 16;
;                 const float rs = __builtin_amdgcn_rsqf(sq[ai][m] * (1.0f / 1024.0f) + RMS_EPS_F), rz = rs * NL2E;
;                 unsigned w[4];
; #pragma unroll
;                 for (int p = 0; p < 4; ++p) {
;                     const f32x4 a0 = acc[ai][0][m][p >> 1], a1 = acc[ai][1][m][p >> 1];
;                     const f32x2 c0 = (p & 1) ? (f32x2){a0[2], a0[3]} : (f32x2){a0[0], a0[1]}, c1 = (p & 1) ? (f32x2){a1[2], a1[3]} : (f32x2){a1[0], a1[1]};
;                     const f32x2 v0 = c0 * rs + b0[p], v1 = c1 * rs + b1[p];
;                     const f32x2 t = (MODE == 0 ? c0 : c1) * rz + bz[p];
;                     f32x2 d; d.x = __builtin_amdgcn_exp2f(t.x); d.y = __builtin_amdgcn_exp2f(t.y); d = d + 1.0f;
;                     f32x2 r; r.x = __builtin_amdgcn_rcpf(d.x); r.y = __builtin_amdgcn_rcpf(d.y);
;                     const f32x2 o = (MODE == 0) ? (v0 * v1) * r : v0 * r;
;                     w[p] = cvt_pk_bf16(o.x, o.y);
;                 }
;                 u32x4 wv; wv.x = w[0]; wv.y = w[1]; wv.z = w[2]; wv.w = w[3];
;                 *(u32x4*)(O + ((unsigned)row * (unsigned)ldc + (unsigned)ocol)) = wv;
	v_pk_fma_f32 v[148:149], v[102:103], v[160:161], v[130:131] op_sel_hi:[1,0,1]
	v_rcp_f32_e32 v170, v170
	v_rcp_f32_e32 v171, v171
	v_pk_fma_f32 v[168:169], v[98:99], v[160:161], v[134:135] op_sel_hi:[1,0,1]
	v_rcp_f32_e32 v172, v172
	v_rcp_f32_e32 v173, v173
	v_pk_mul_f32 v[148:149], v[148:149], v[168:169]
	v_pk_fma_f32 v[168:169], v[104:105], v[160:161], v[132:133] op_sel_hi:[1,0,1]
	v_pk_mul_f32 v[148:149], v[148:149], v[170:171]
	v_pk_fma_f32 v[170:171], v[100:101], v[160:161], v[136:137] op_sel_hi:[1,0,1]
	v_cvt_pk_bf16_f32 v148, v148, v149
	s_nop 0
	v_pk_mul_f32 v[168:169], v[168:169], v[170:171]
	s_nop 0
	v_pk_mul_f32 v[168:169], v[168:169], v[172:173]
	s_nop 0
	v_cvt_pk_bf16_f32 v149, v168, v169
	v_lshl_add_u64 v[168:169], v[158:159], 1, s[42:43]
	global_store_dwordx4 v[168:169], v[146:149], off
	v_add_u32_e32 v158, s12, v158
	s_nop 0
	v_fmamk_f32 v146, v167, 0x3a800000, v213
	v_rsq_f32_e32 v160, v146
	s_nop 0
	v_mul_f32_e32 v162, 0xbfb8aa3b, v160
	v_pk_fma_f32 v[168:169], v[94:95], v[162:163], v[156:157] op_sel_hi:[1,0,1]
	v_pk_fma_f32 v[170:171], v[96:97], v[162:163], v[154:155] op_sel_hi:[1,0,1]
	v_exp_f32_e32 v168, v168
	v_exp_f32_e32 v169, v169
	v_exp_f32_e32 v170, v170
	v_exp_f32_e32 v171, v171
	v_pk_fma_f32 v[146:147], v[94:95], v[160:161], v[138:139] op_sel_hi:[1,0,1]
	v_pk_add_f32 v[168:169], v[168:169], 1.0 op_sel_hi:[1,0]
	v_pk_fma_f32 v[148:149], v[90:91], v[160:161], v[142:143] op_sel_hi:[1,0,1]
	v_rcp_f32_e32 v168, v168
	v_rcp_f32_e32 v169, v169
	v_pk_add_f32 v[170:171], v[170:171], 1.0 op_sel_hi:[1,0]
	v_pk_mul_f32 v[146:147], v[146:147], v[148:149]
	v_rcp_f32_e32 v170, v170
	v_rcp_f32_e32 v171, v171
	v_pk_mul_f32 v[146:147], v[146:147], v[168:169]
	v_pk_fma_f32 v[148:149], v[96:97], v[160:161], v[140:141] op_sel_hi:[1,0,1]
	v_pk_fma_f32 v[168:169], v[92:93], v[160:161], v[144:145] op_sel_hi:[1,0,1]
	v_pk_fma_f32 v[172:173], v[88:89], v[162:163], v[150:151] op_sel_hi:[1,0,1]
	v_pk_mul_f32 v[148:149], v[148:149], v[168:169]
	v_exp_f32_e32 v172, v172
	v_pk_mul_f32 v[148:149], v[148:149], v[170:171]
	v_pk_fma_f32 v[170:171], v[86:87], v[162:163], v[152:153] op_sel_hi:[1,0,1]
	v_exp_f32_e32 v173, v173
	v_exp_f32_e32 v170, v170
	v_exp_f32_e32 v171, v171
	v_cvt_pk_bf16_f32 v146, v146, v147
	v_pk_add_f32 v[172:173], v[172:173], 1.0 op_sel_hi:[1,0]
	v_cvt_pk_bf16_f32 v147, v148, v149
	v_pk_add_f32 v[170:171], v[170:171], 1.0 op_sel_hi:[1,0]
	v_pk_fma_f32 v[148:149], v[86:87], v[160:161], v[130:131] op_sel_hi:[1,0,1]
	v_rcp_f32_e32 v170, v170
	v_rcp_f32_e32 v171, v171
	v_pk_fma_f32 v[168:169], v[82:83], v[160:161], v[134:135] op_sel_hi:[1,0,1]
	v_rcp_f32_e32 v172, v172
	v_rcp_f32_e32 v173, v173
	v_pk_mul_f32 v[148:149], v[148:149], v[168:169]
	v_pk_fma_f32 v[168:169], v[88:89], v[160:161], v[132:133] op_sel_hi:[1,0,1]
	v_pk_mul_f32 v[148:149], v[148:149], v[170:171]
	v_pk_fma_f32 v[170:171], v[84:85], v[160:161], v[136:137] op_sel_hi:[1,0,1]
	v_cvt_pk_bf16_f32 v148, v148, v149
	s_nop 0
	v_pk_mul_f32 v[168:169], v[168:169], v[170:171]
	s_nop 0
	v_pk_mul_f32 v[168:169], v[168:169], v[172:173]
	s_nop 0
	v_cvt_pk_bf16_f32 v149, v168, v169
	v_lshl_add_u64 v[168:169], v[158:159], 1, s[42:43]
	global_store_dwordx4 v[168:169], v[146:149], off
	v_add_u32_e32 v158, s12, v158
	s_nop 0
	v_fmamk_f32 v146, v166, 0x3a800000, v213
	v_rsq_f32_e32 v160, v146
	s_nop 0
	v_mul_f32_e32 v162, 0xbfb8aa3b, v160
	v_pk_fma_f32 v[166:167], v[78:79], v[162:163], v[156:157] op_sel_hi:[1,0,1]
	v_pk_fma_f32 v[168:169], v[80:81], v[162:163], v[154:155] op_sel_hi:[1,0,1]
	v_exp_f32_e32 v166, v166
	v_exp_f32_e32 v167, v167
	v_exp_f32_e32 v168, v168
	v_exp_f32_e32 v169, v169
	v_pk_fma_f32 v[146:147], v[78:79], v[160:161], v[138:139] op_sel_hi:[1,0,1]
	v_pk_add_f32 v[166:167], v[166:167], 1.0 op_sel_hi:[1,0]
	v_pk_fma_f32 v[148:149], v[74:75], v[160:161], v[142:143] op_sel_hi:[1,0,1]
	v_rcp_f32_e32 v166, v166
	v_rcp_f32_e32 v167, v167
	v_pk_add_f32 v[168:169], v[168:169], 1.0 op_sel_hi:[1,0]
	v_pk_mul_f32 v[146:147], v[146:147], v[148:149]
	v_rcp_f32_e32 v168, v168
	v_rcp_f32_e32 v169, v169
	v_pk_mul_f32 v[146:147], v[146:147], v[166:167]
	v_pk_fma_f32 v[148:149], v[80:81], v[160:161], v[140:141] op_sel_hi:[1,0,1]
	v_pk_fma_f32 v[166:167], v[76:77], v[160:161], v[144:145] op_sel_hi:[1,0,1]
	v_pk_fma_f32 v[170:171], v[72:73], v[162:163], v[150:151] op_sel_hi:[1,0,1]
	v_pk_mul_f32 v[148:149], v[148:149], v[166:167]
	v_exp_f32_e32 v170, v170
	v_pk_mul_f32 v[148:149], v[148:149], v[168:169]
	v_pk_fma_f32 v[168:169], v[70:71], v[162:163], v[152:153] op_sel_hi:[1,0,1]
	v_exp_f32_e32 v171, v171
	v_exp_f32_e32 v168, v168
	v_exp_f32_e32 v169, v169
	v_cvt_pk_bf16_f32 v146, v146, v147
	v_pk_add_f32 v[170:171], v[170:171], 1.0 op_sel_hi:[1,0]
	v_cvt_pk_bf16_f32 v147, v148, v149
	v_pk_add_f32 v[168:169], v[168:169], 1.0 op_sel_hi:[1,0]
	v_pk_fma_f32 v[148:149], v[70:71], v[160:161], v[130:131] op_sel_hi:[1,0,1]
	v_rcp_f32_e32 v168, v168
	v_rcp_f32_e32 v169, v169
	v_pk_fma_f32 v[166:167], v[66:67], v[160:161], v[134:135] op_sel_hi:[1,0,1]
	v_rcp_f32_e32 v170, v170
	v_rcp_f32_e32 v171, v171
	v_pk_mul_f32 v[148:149], v[148:149], v[166:167]
	v_pk_fma_f32 v[166:167], v[72:73], v[160:161], v[132:133] op_sel_hi:[1,0,1]
	v_pk_mul_f32 v[148:149], v[148:149], v[168:169]
	v_pk_fma_f32 v[168:169], v[68:69], v[160:161], v[136:137] op_sel_hi:[1,0,1]
	v_cvt_pk_bf16_f32 v148, v148, v149
	s_nop 0
	v_pk_mul_f32 v[166:167], v[166:167], v[168:169]
	s_nop 0
	v_pk_mul_f32 v[166:167], v[166:167], v[170:171]
	s_nop 0
	v_cvt_pk_bf16_f32 v149, v166, v167
	v_lshl_add_u64 v[166:167], v[158:159], 1, s[42:43]
	global_store_dwordx4 v[166:167], v[146:149], off
	v_add_u32_e32 v158, s17, v158
	s_nop 0
; __device__ __forceinline__ unsigned cvt_pk_bf16(float lo, float hi) { unsigned r; asm volatile("v_cvt_pk_bf16_f32 %0, %1, %2" : "=v"(r) : "v"(lo), "v"(hi)); return r; }
;     __device__ __forceinline__ void operator()(const f32x4 (&acc)[2][2][4][2], const Unit& u, int wr, int wc, int fr, int fq) const {
;     ...
;             for (int m = 0; m < 4; ++m) {
;                 const int row = row0 + ai * HALF + m * 16;
;                 const float rs = __builtin_amdgcn_rsqf(sq[ai][m] * (1.0f / 1024.0f) + RMS_EPS_F), rz = rs * NL2E;
;                 unsigned w[4];
; #pragma unroll
;                 for (int p = 0; p < 4; ++p) {
;                     const f32x4 a0 = acc[ai][0][m][p >> 1], a1 = acc[ai][1][m][p >> 1];
;                     const f32x2 c0 = (p & 1) ? (f32x2){a0[2], a0[3]} : (f32x2){a0[0], a0[1]}, c1 = (p & 1) ? (f32x2){a1[2], a1[3]} : (f32x2){a1[0], a1[1]};
;                     const f32x2 v0 = c0 * rs + b0[p], v1 = c1 * rs + b1[p];
;                     const f32x2 t = (MODE == 0 ? c0 : c1) * rz + bz[p];
;                     f32x2 d; d.x = __builtin_amdgcn_exp2f(t.x); d.y = __builtin_amdgcn_exp2f(t.y); d = d + 1.0f;
;                     f32x2 r; r.x = __builtin_amdgcn_rcpf(d.x); r.y = __builtin_amdgcn_rcpf(d.y);
;                     const f32x2 o = (MODE == 0) ? (v0 * v1) * r : v0 * r;
;                     w[p] = cvt_pk_bf16(o.x, o.y);
;                 }
;                 u32x4 wv; wv.x = w[0]; wv.y = w[1]; wv.z = w[2]; wv.w = w[3];
;                 *(u32x4*)(O + ((unsigned)row * (unsigned)ldc + (unsigned)ocol)) = wv;
	v_fmamk_f32 v146, v165, 0x3a800000, v213
	v_rsq_f32_e32 v160, v146
	s_nop 0
	v_mul_f32_e32 v162, 0xbfb8aa3b, v160
	v_pk_fma_f32 v[166:167], v[62:63], v[162:163], v[156:157] op_sel_hi:[1,0,1]
	v_pk_fma_f32 v[168:169], v[64:65], v[162:163], v[154:155] op_sel_hi:[1,0,1]
	v_exp_f32_e32 v166, v166
	v_exp_f32_e32 v167, v167
	v_exp_f32_e32 v168, v168
	v_exp_f32_e32 v169, v169
	v_pk_fma_f32 v[146:147], v[62:63], v[160:161], v[138:139] op_sel_hi:[1,0,1]
	v_pk_add_f32 v[166:167], v[166:167], 1.0 op_sel_hi:[1,0]
	v_pk_fma_f32 v[148:149], v[58:59], v[160:161], v[142:143] op_sel_hi:[1,0,1]
	v_rcp_f32_e32 v166, v166
	v_rcp_f32_e32 v167, v167
	v_pk_add_f32 v[168:169], v[168:169], 1.0 op_sel_hi:[1,0]
	v_pk_mul_f32 v[146:147], v[146:147], v[148:149]
	v_rcp_f32_e32 v168, v168
	v_rcp_f32_e32 v169, v169
	v_pk_mul_f32 v[146:147], v[146:147], v[166:167]
	v_pk_fma_f32 v[148:149], v[64:65], v[160:161], v[140:141] op_sel_hi:[1,0,1]
	v_pk_fma_f32 v[166:167], v[60:61], v[160:161], v[144:145] op_sel_hi:[1,0,1]
	v_pk_fma_f32 v[170:171], v[56:57], v[162:163], v[150:151] op_sel_hi:[1,0,1]
	v_pk_mul_f32 v[148:149], v[148:149], v[166:167]
	v_exp_f32_e32 v170, v170
	v_pk_mul_f32 v[148:149], v[148:149], v[168:169]
	v_pk_fma_f32 v[168:169], v[54:55], v[162:163], v[152:153] op_sel_hi:[1,0,1]
	v_exp_f32_e32 v171, v171
	v_exp_f32_e32 v168, v168
	v_exp_f32_e32 v169, v169
	v_cvt_pk_bf16_f32 v146, v146, v147
	v_pk_add_f32 v[170:171], v[170:171], 1.0 op_sel_hi:[1,0]
	v_cvt_pk_bf16_f32 v147, v148, v149
	v_pk_add_f32 v[168:169], v[168:169], 1.0 op_sel_hi:[1,0]
	v_pk_fma_f32 v[148:149], v[54:55], v[160:161], v[130:131] op_sel_hi:[1,0,1]
	v_rcp_f32_e32 v168, v168
	v_rcp_f32_e32 v169, v169
	v_pk_fma_f32 v[166:167], v[50:51], v[160:161], v[134:135] op_sel_hi:[1,0,1]
	v_rcp_f32_e32 v170, v170
	v_rcp_f32_e32 v171, v171
	v_pk_mul_f32 v[148:149], v[148:149], v[166:167]
	v_pk_fma_f32 v[166:167], v[56:57], v[160:161], v[132:133] op_sel_hi:[1,0,1]
	v_pk_mul_f32 v[148:149], v[148:149], v[168:169]
	v_pk_fma_f32 v[168:169], v[52:53], v[160:161], v[136:137] op_sel_hi:[1,0,1]
	v_cvt_pk_bf16_f32 v148, v148, v149
	s_nop 0
	v_pk_mul_f32 v[166:167], v[166:167], v[168:169]
	s_nop 0
	v_pk_mul_f32 v[166:167], v[166:167], v[170:171]
	s_nop 0
	v_cvt_pk_bf16_f32 v149, v166, v167
	v_lshl_add_u64 v[166:167], v[158:159], 1, s[42:43]
	global_store_dwordx4 v[166:167], v[146:149], off
	v_add_u32_e32 v158, s12, v158
	s_nop 0
	v_fmamk_f32 v146, v164, 0x3a800000, v213
	v_rsq_f32_e32 v160, v146
	s_nop 0
	v_mul_f32_e32 v162, 0xbfb8aa3b, v160
	v_pk_fma_f32 v[164:165], v[46:47], v[162:163], v[156:157] op_sel_hi:[1,0,1]
	v_pk_fma_f32 v[166:167], v[48:49], v[162:163], v[154:155] op_sel_hi:[1,0,1]
	v_exp_f32_e32 v164, v164
	v_exp_f32_e32 v165, v165
	v_exp_f32_e32 v166, v166
	v_exp_f32_e32 v167, v167
	v_pk_fma_f32 v[146:147], v[46:47], v[160:161], v[138:139] op_sel_hi:[1,0,1]
	v_pk_add_f32 v[164:165], v[164:165], 1.0 op_sel_hi:[1,0]
	v_pk_fma_f32 v[148:149], v[42:43], v[160:161], v[142:143] op_sel_hi:[1,0,1]
	v_rcp_f32_e32 v164, v164
	v_rcp_f32_e32 v165, v165
	v_pk_add_f32 v[166:167], v[166:167], 1.0 op_sel_hi:[1,0]
	v_pk_mul_f32 v[146:147], v[146:147], v[148:149]
	v_rcp_f32_e32 v166, v166
	v_rcp_f32_e32 v167, v167
	v_pk_mul_f32 v[146:147], v[146:147], v[164:165]
	v_pk_fma_f32 v[148:149], v[48:49], v[160:161], v[140:141] op_sel_hi:[1,0,1]
	v_pk_fma_f32 v[164:165], v[44:45], v[160:161], v[144:145] op_sel_hi:[1,0,1]
	v_pk_fma_f32 v[168:169], v[40:41], v[162:163], v[150:151] op_sel_hi:[1,0,1]
	v_pk_mul_f32 v[148:149], v[148:149], v[164:165]
	v_exp_f32_e32 v168, v168
	v_pk_mul_f32 v[148:149], v[148:149], v[166:167]
	v_pk_fma_f32 v[166:167], v[38:39], v[162:163], v[152:153] op_sel_hi:[1,0,1]
	v_exp_f32_e32 v169, v169
	v_exp_f32_e32 v166, v166
	v_exp_f32_e32 v167, v167
	v_cvt_pk_bf16_f32 v146, v146, v147
	v_pk_add_f32 v[168:169], v[168:169], 1.0 op_sel_hi:[1,0]
	v_cvt_pk_bf16_f32 v147, v148, v149
	v_pk_add_f32 v[166:167], v[166:167], 1.0 op_sel_hi:[1,0]
	v_pk_fma_f32 v[148:149], v[38:39], v[160:161], v[130:131] op_sel_hi:[1,0,1]
	v_rcp_f32_e32 v166, v166
	v_rcp_f32_e32 v167, v167
	v_pk_fma_f32 v[164:165], v[34:35], v[160:161], v[134:135] op_sel_hi:[1,0,1]
	v_rcp_f32_e32 v168, v168
	v_rcp_f32_e32 v169, v169
	v_pk_mul_f32 v[148:149], v[148:149], v[164:165]
	v_pk_fma_f32 v[164:165], v[40:41], v[160:161], v[132:133] op_sel_hi:[1,0,1]
	v_pk_mul_f32 v[148:149], v[148:149], v[166:167]
	v_pk_fma_f32 v[166:167], v[36:37], v[160:161], v[136:137] op_sel_hi:[1,0,1]
	v_cvt_pk_bf16_f32 v148, v148, v149
	s_nop 0
	v_pk_mul_f32 v[164:165], v[164:165], v[166:167]
	s_nop 0
	v_pk_mul_f32 v[164:165], v[164:165], v[168:169]
	s_nop 0
	v_cvt_pk_bf16_f32 v149, v164, v165
	v_lshl_add_u64 v[164:165], v[158:159], 1, s[42:43]
	global_store_dwordx4 v[164:165], v[146:149], off
	v_add_u32_e32 v158, s12, v158
	s_nop 0
; __device__ __forceinline__ unsigned cvt_pk_bf16(float lo, float hi) { unsigned r; asm volatile("v_cvt_pk_bf16_f32 %0, %1, %2" : "=v"(r) : "v"(lo), "v"(hi)); return r; }
;     __device__ __forceinline__ void operator()(const f32x4 (&acc)[2][2][4][2], const Unit& u, int wr, int wc, int fr, int fq) const {
;     ...
;             for (int m = 0; m < 4; ++m) {
;                 const int row = row0 + ai * HALF + m * 16;
;                 const float rs = __builtin_amdgcn_rsqf(sq[ai][m] * (1.0f / 1024.0f) + RMS_EPS_F), rz = rs * NL2E;
;                 unsigned w[4];
; #pragma unroll
;                 for (int p = 0; p < 4; ++p) {
;                     const f32x4 a0 = acc[ai][0][m][p >> 1], a1 = acc[ai][1][m][p >> 1];
;                     const f32x2 c0 = (p & 1) ? (f32x2){a0[2], a0[3]} : (f32x2){a0[0], a0[1]}, c1 = (p & 1) ? (f32x2){a1[2], a1[3]} : (f32x2){a1[0], a1[1]};
;                     const f32x2 v0 = c0 * rs + b0[p], v1 = c1 * rs + b1[p];
;                     const f32x2 t = (MODE == 0 ? c0 : c1) * rz + bz[p];
;                     f32x2 d; d.x = __builtin_amdgcn_exp2f(t.x); d.y = __builtin_amdgcn_exp2f(t.y); d = d + 1.0f;
;                     f32x2 r; r.x = __builtin_amdgcn_rcpf(d.x); r.y = __builtin_amdgcn_rcpf(d.y);
;                     const f32x2 o = (MODE == 0) ? (v0 * v1) * r : v0 * r;
;                     w[p] = cvt_pk_bf16(o.x, o.y);
;                 }
;                 u32x4 wv; wv.x = w[0]; wv.y = w[1]; wv.z = w[2]; wv.w = w[3];
;                 *(u32x4*)(O + ((unsigned)row * (unsigned)ldc + (unsigned)ocol)) = wv;
	v_fmamk_f32 v146, v163, 0x3a800000, v213
	v_rsq_f32_e32 v160, v146
	s_nop 0
	v_mul_f32_e32 v162, 0xbfb8aa3b, v160
	v_pk_fma_f32 v[164:165], v[30:31], v[162:163], v[156:157] op_sel_hi:[1,0,1]
	v_pk_fma_f32 v[166:167], v[32:33], v[162:163], v[154:155] op_sel_hi:[1,0,1]
	v_exp_f32_e32 v164, v164
	v_exp_f32_e32 v165, v165
	v_exp_f32_e32 v166, v166
	v_exp_f32_e32 v167, v167
	v_pk_fma_f32 v[146:147], v[30:31], v[160:161], v[138:139] op_sel_hi:[1,0,1]
	v_pk_add_f32 v[164:165], v[164:165], 1.0 op_sel_hi:[1,0]
	v_pk_fma_f32 v[148:149], v[26:27], v[160:161], v[142:143] op_sel_hi:[1,0,1]
	v_rcp_f32_e32 v164, v164
	v_rcp_f32_e32 v165, v165
	v_pk_add_f32 v[166:167], v[166:167], 1.0 op_sel_hi:[1,0]
	v_pk_mul_f32 v[146:147], v[146:147], v[148:149]
	v_rcp_f32_e32 v166, v166
	v_rcp_f32_e32 v167, v167
	v_pk_mul_f32 v[146:147], v[146:147], v[164:165]
	v_pk_fma_f32 v[148:149], v[32:33], v[160:161], v[140:141] op_sel_hi:[1,0,1]
	v_pk_fma_f32 v[164:165], v[28:29], v[160:161], v[144:145] op_sel_hi:[1,0,1]
	v_cvt_pk_bf16_f32 v146, v146, v147
	s_nop 0
	v_pk_mul_f32 v[148:149], v[148:149], v[164:165]
	v_pk_fma_f32 v[164:165], v[18:19], v[160:161], v[134:135] op_sel_hi:[1,0,1]
	v_pk_mul_f32 v[148:149], v[148:149], v[166:167]
	v_pk_fma_f32 v[166:167], v[22:23], v[162:163], v[152:153] op_sel_hi:[1,0,1]
	v_pk_fma_f32 v[162:163], v[24:25], v[162:163], v[150:151] op_sel_hi:[1,0,1]
	v_exp_f32_e32 v166, v166
	v_exp_f32_e32 v167, v167
	v_exp_f32_e32 v162, v162
	v_exp_f32_e32 v163, v163
	v_cvt_pk_bf16_f32 v147, v148, v149
	v_pk_add_f32 v[166:167], v[166:167], 1.0 op_sel_hi:[1,0]
	v_pk_fma_f32 v[148:149], v[22:23], v[160:161], v[130:131] op_sel_hi:[1,0,1]
	v_rcp_f32_e32 v166, v166
	v_rcp_f32_e32 v167, v167
	v_pk_add_f32 v[162:163], v[162:163], 1.0 op_sel_hi:[1,0]
	v_pk_mul_f32 v[148:149], v[148:149], v[164:165]
	v_rcp_f32_e32 v162, v162
	v_rcp_f32_e32 v163, v163
	v_pk_mul_f32 v[148:149], v[148:149], v[166:167]
	v_pk_fma_f32 v[164:165], v[24:25], v[160:161], v[132:133] op_sel_hi:[1,0,1]
	v_pk_fma_f32 v[166:167], v[20:21], v[160:161], v[136:137] op_sel_hi:[1,0,1]
	v_cvt_pk_bf16_f32 v148, v148, v149
	s_nop 0
	v_pk_mul_f32 v[164:165], v[164:165], v[166:167]
	s_nop 0
	v_pk_mul_f32 v[162:163], v[164:165], v[162:163]
	s_nop 0
	v_cvt_pk_bf16_f32 v149, v162, v163
	v_lshl_add_u64 v[162:163], v[158:159], 1, s[42:43]
	global_store_dwordx4 v[162:163], v[146:149], off
	s_nop 1
	v_fmamk_f32 v146, v161, 0x3a800000, v213
	v_rsq_f32_e32 v146, v146
	s_nop 0
	v_mul_f32_e32 v148, 0xbfb8aa3b, v146
	v_pk_fma_f32 v[138:139], v[14:15], v[146:147], v[138:139] op_sel_hi:[1,0,1]
	v_pk_fma_f32 v[142:143], v[10:11], v[146:147], v[142:143] op_sel_hi:[1,0,1]
	v_pk_fma_f32 v[156:157], v[14:15], v[148:149], v[156:157] op_sel_hi:[1,0,1]
	v_pk_mul_f32 v[138:139], v[138:139], v[142:143]
	v_pk_fma_f32 v[142:143], v[12:13], v[146:147], v[144:145] op_sel_hi:[1,0,1]
	v_pk_fma_f32 v[144:145], v[16:17], v[148:149], v[154:155] op_sel_hi:[1,0,1]
	v_exp_f32_e32 v156, v156
	v_exp_f32_e32 v157, v157
	v_exp_f32_e32 v144, v144
	v_exp_f32_e32 v145, v145
	v_pk_fma_f32 v[140:141], v[16:17], v[146:147], v[140:141] op_sel_hi:[1,0,1]
	v_pk_add_f32 v[156:157], v[156:157], 1.0 op_sel_hi:[1,0]
	v_pk_mul_f32 v[140:141], v[140:141], v[142:143]
	v_pk_add_f32 v[144:145], v[144:145], 1.0 op_sel_hi:[1,0]
	v_rcp_f32_e32 v156, v156
	v_rcp_f32_e32 v157, v157
	v_rcp_f32_e32 v144, v144
	v_rcp_f32_e32 v145, v145
	v_pk_fma_f32 v[130:131], v[6:7], v[146:147], v[130:131] op_sel_hi:[1,0,1]
	v_pk_mul_f32 v[138:139], v[138:139], v[156:157]
	v_pk_fma_f32 v[134:135], v[2:3], v[146:147], v[134:135] op_sel_hi:[1,0,1]
	v_pk_mul_f32 v[140:141], v[140:141], v[144:145]
	v_cvt_pk_bf16_f32 v138, v138, v139
	v_pk_mul_f32 v[130:131], v[130:131], v[134:135]
	v_cvt_pk_bf16_f32 v139, v140, v141
	v_pk_fma_f32 v[140:141], v[6:7], v[148:149], v[152:153] op_sel_hi:[1,0,1]
	v_pk_fma_f32 v[134:135], v[8:9], v[148:149], v[150:151] op_sel_hi:[1,0,1]
	v_exp_f32_e32 v140, v140
	v_exp_f32_e32 v141, v141
	v_exp_f32_e32 v134, v134
	v_exp_f32_e32 v135, v135
	v_pk_add_f32 v[140:141], v[140:141], 1.0 op_sel_hi:[1,0]
	s_nop 0
	v_rcp_f32_e32 v140, v140
	v_rcp_f32_e32 v141, v141
	v_pk_add_f32 v[134:135], v[134:135], 1.0 op_sel_hi:[1,0]
	v_pk_mul_f32 v[130:131], v[130:131], v[140:141]
	v_rcp_f32_e32 v134, v134
	v_rcp_f32_e32 v135, v135
	v_cvt_pk_bf16_f32 v140, v130, v131
	v_pk_fma_f32 v[130:131], v[8:9], v[146:147], v[132:133] op_sel_hi:[1,0,1]
	v_pk_fma_f32 v[132:133], v[4:5], v[146:147], v[136:137] op_sel_hi:[1,0,1]
	s_nop 0
	v_pk_mul_f32 v[130:131], v[130:131], v[132:133]
	s_nop 0
	v_pk_mul_f32 v[130:131], v[130:131], v[134:135]
	s_nop 0
	v_cvt_pk_bf16_f32 v141, v130, v131
	v_add_u32_e32 v130, s12, v158
	v_mov_b32_e32 v131, v0
	v_lshl_add_u64 v[130:131], v[130:131], 1, s[42:43]
	s_mov_b64 s[42:43], 0
	global_store_dwordx4 v[130:131], v[138:141], off
